# FoX: waves whose last band tiles are entirely future keys skip the final step (waves 0-3) and the drain (waves 0-5)
# speedup vs baseline: 1.0050x; 1.0050x over previous
;   #define RESC() do{ if(resc){ asm volatile("s_waitcnt lgkmcnt(0)":::"memory"); \
;       _Pragma("unroll") for(int d_=0;d_<2;++d_) _Pragma("unroll") for(int r=0;r<16;++r)o[d_][r]*=wsf[crow(r,hi)]; } }while(0)
;   #define ROT() do{sl_prev=sl_cur;sl_cur=sl_next;sl_next=(sl_next==(NSLOT-1)*SLOTB)?0:sl_next+SLOTB;}while(0)
;   #define ENDW(tt) do{ if((tt)+3<NT){WAIT_BAR(2);} else if((tt)+2<NT){WAIT_BAR(1);} else {WAIT_BAR(0);} }while(0)
; template<int THRL,int MODE,int DM,bool DRY=false> __device__ __forceinline__ void attn_unit(int b,int h,int qb,const bf16*Q,const bf16*__restrict__ K,const bf16*__restrict__ V,bf16*O,const bf16*__restrict__ Z,const float*__restrict__ XP,const int*__restrict__ TS,volatile unsigned*lw,unsigned nxt,cha ...
;     ...
;     STEP(pB0,pB1,pA0,pA1,t,(t+3<NT),(t+1<NT),(t+1<NT));       ENDW(t);   RESC(); ROT();
;     STEP(pA0,pA1,pB0,pB1,t+1,(t+4<NT),(t+2<NT),(t+2<NT));     ENDW(t+1); RESC(); ROT();
;   }
;   STEP(pB0,pB1,pA0,pA1,NT-1,false,false,false); RESC();
.LBB0_1521:
	s_cmp_gt_u32 s81, 3
	s_cbranch_scc1 .Lfox_fin_go
	v_mov_b32_e32 v82, v223
	v_lshl_add_u32 v83, v213, 2, s16
	s_branch .LBB0_1524

; #define SBAR() __builtin_amdgcn_sched_barrier(0)
;   #define PKW(P,B) cvtpk_s(P[B],P[B+1])
; template<int THRL,int MODE,int DM,bool DRY=false> __device__ __forceinline__ void attn_unit(int b,int h,int qb,const bf16*Q,const bf16*__restrict__ K,const bf16*__restrict__ V,bf16*O,const bf16*__restrict__ Z,const float*__restrict__ XP,const int*__restrict__ TS,volatile unsigned*lw,unsigned nxt,cha ...
;     ...
;   const bf16*Zw=Z+(rowbase+q0+wid*QBLK)*DM+h*D; u32x4 zpre[4];
;   #pragma unroll
;   for(int i=0;i<4;++i)zpre[i]=*(const u32x4*)(Zw+(long)(i*8+(lane>>3))*DM+(lane&7)*8);
;   { float sacc=pB0[0]+pB0[1]; _Pragma("unroll") for(int r=2;r<16;++r)sacc+=pB0[r]; _Pragma("unroll") for(int r=0;r<16;++r)sacc+=pB1[r]; l_reg+=sacc;
;     pw0=(u32x4){PKW(pB0,0),PKW(pB0,2),PKW(pB0,4),PKW(pB0,6)};pw1=(u32x4){PKW(pB0,8),PKW(pB0,10),PKW(pB0,12),PKW(pB0,14)};pw2=(u32x4){PKW(pB1,0),PKW(pB1,2),PKW(pB1,4),PKW(pB1,6)};pw3=(u32x4){PKW(pB1,8),PKW(pB1,10),PKW(pB1,12),PKW(pB1,14)};
;     SBAR(); pv(o,vb0+sl_cur,PAF(0),PAF(1),PAF(2),PAF(3)); }
;     ...
;   if(lw!=nullptr&&tid==0)lw[0]=nxt;
.LBB0_1524:
	s_cmp_lg_u32 0, -1
	s_cselect_b32 s8, 0, 0
	s_add_i32 s10, s8, 0x6000
	s_add_u32 s8, s73, s52
	s_addc_u32 s9, s74, s53
	s_add_u32 s8, s8, s54
	v_lshrrev_b32_e32 v84, 3, v210
	v_and_b32_e32 v64, 56, v212
	s_addc_u32 s9, s9, s55
	v_lshlrev_b32_e32 v192, 1, v64
	v_mul_u32_u24_e32 v66, 0x1c00, v84
	v_lshl_add_u64 v[64:65], s[8:9], 0, v[192:193]
	v_lshlrev_b32_e32 v80, 1, v66
	v_mov_b32_e32 v81, v193
	v_lshl_add_u64 v[64:65], v[64:65], 0, v[80:81]
	v_add_co_u32_e32 v66, vcc, s78, v64
	v_add3_u32 v81, v217, s10, v211
	s_nop 0
	v_addc_co_u32_e32 v67, vcc, 0, v65, vcc
	flat_load_dwordx4 v[76:79], v[64:65]
	flat_load_dwordx4 v[72:75], v[66:67]
	v_add_co_u32_e32 v66, vcc, s79, v64
	v_cvt_pk_bf16_f32 v86, v48, v49
	s_nop 0
	v_addc_co_u32_e32 v67, vcc, 0, v65, vcc
	v_add_co_u32_e32 v64, vcc, s80, v64
	v_cvt_pk_bf16_f32 v87, v50, v51
	s_nop 0
	v_addc_co_u32_e32 v65, vcc, 0, v65, vcc
	flat_load_dwordx4 v[68:71], v[66:67]
	s_nop 0
	flat_load_dwordx4 v[64:67], v[64:65]
	s_cmp_gt_u32 s81, 5
	s_cbranch_scc1 .Lfox_drain_go
	v_cmp_eq_u32_e32 vcc, 0, v207
	s_and_b64 s[10:11], s[20:21], vcc
	s_and_saveexec_b64 s[8:9], s[10:11]
	s_cbranch_execz .Lfox_dr_1
	s_mov_b64 s[10:11], src_shared_base
	s_cmp_lg_u32 s3, -1
	s_cselect_b32 s10, s3, 0
	s_cselect_b32 s11, s11, 0
	v_mov_b32_e32 v86, s10
	v_mov_b32_e32 v87, s11
	flat_store_dword v[86:87], v206 sc0 sc1
	s_waitcnt vmcnt(0)
.Lfox_dr_1:
	s_or_b64 exec, exec, s[8:9]
	v_mov_b32_e32 v32, v82
	s_branch .Lfox_drain_join
.Lfox_drain_go:
	v_cvt_pk_bf16_f32 v88, v52, v53
	v_cvt_pk_bf16_f32 v89, v54, v55
	v_cvt_pk_bf16_f32 v90, v56, v57
	v_cvt_pk_bf16_f32 v91, v58, v59
	v_cvt_pk_bf16_f32 v92, v60, v61
	v_cvt_pk_bf16_f32 v93, v62, v63
	v_cvt_pk_bf16_f32 v94, v32, v33
	v_cvt_pk_bf16_f32 v95, v34, v35
	v_cvt_pk_bf16_f32 v96, v36, v37
	v_cvt_pk_bf16_f32 v97, v38, v39
	v_cvt_pk_bf16_f32 v98, v40, v41
	v_cvt_pk_bf16_f32 v99, v42, v43
	v_cvt_pk_bf16_f32 v100, v44, v45
	v_cvt_pk_bf16_f32 v101, v46, v47
	v_add3_u32 v81, v81, v216, s65
	ds_read_b64_tr_b16 v[102:103],v81 offset:0
	ds_read_b64_tr_b16 v[104:105],v81 offset:512
	ds_read_b64_tr_b16 v[106:107],v81 offset:1024
	ds_read_b64_tr_b16 v[108:109],v81 offset:1536
	ds_read_b64_tr_b16 v[110:111],v81 offset:2048
	ds_read_b64_tr_b16 v[112:113],v81 offset:2560
	ds_read_b64_tr_b16 v[114:115],v81 offset:3072
	ds_read_b64_tr_b16 v[116:117],v81 offset:3584
	s_waitcnt lgkmcnt(0)
	s_nop 0
	v_mfma_f32_32x32x16_bf16 v[16:31], v[86:89], v[102:105], v[16:31]
	ds_read_b64_tr_b16 v[102:103],v81 offset:4096
	ds_read_b64_tr_b16 v[104:105],v81 offset:4608
	v_mfma_f32_32x32x16_bf16 v[16:31], v[90:93], v[106:109], v[16:31]
	ds_read_b64_tr_b16 v[106:107],v81 offset:5120
	ds_read_b64_tr_b16 v[108:109],v81 offset:5632
	v_mfma_f32_32x32x16_bf16 v[16:31], v[94:97], v[110:113], v[16:31]
	ds_read_b64_tr_b16 v[110:111],v81 offset:6144
	ds_read_b64_tr_b16 v[112:113],v81 offset:6656
	ds_read_b64_tr_b16 v[118:119],v81 offset:7168
	ds_read_b64_tr_b16 v[120:121],v81 offset:7680
	s_waitcnt lgkmcnt(0)
	v_mfma_f32_32x32x16_bf16 v[16:31], v[98:101], v[114:117], v[16:31]
	v_mfma_f32_32x32x16_bf16 v[0:15], v[86:89], v[102:105], v[0:15]
	v_cmp_eq_u32_e32 vcc, 0, v207
	s_and_b64 s[10:11], s[20:21], vcc
	v_mfma_f32_32x32x16_bf16 v[0:15], v[90:93], v[106:109], v[0:15]
	v_mfma_f32_32x32x16_bf16 v[0:15], v[94:97], v[110:113], v[0:15]
	v_mfma_f32_32x32x16_bf16 v[0:15], v[98:101], v[118:121], v[0:15]
	s_and_saveexec_b64 s[8:9], s[10:11]
	s_cbranch_execz .LBB0_1526
	s_mov_b64 s[10:11], src_shared_base
	s_cmp_lg_u32 s3, -1
	s_cselect_b32 s10, s3, 0
	s_cselect_b32 s11, s11, 0
	v_mov_b32_e32 v86, s10
	v_mov_b32_e32 v87, s11
	flat_store_dword v[86:87], v206 sc0 sc1
	s_waitcnt vmcnt(0)

; template<int THRL,int MODE,int DM,bool DRY=false> __device__ __forceinline__ void attn_unit(int b,int h,int qb,const bf16*Q,const bf16*__restrict__ K,const bf16*__restrict__ V,bf16*O,const bf16*__restrict__ Z,const float*__restrict__ XP,const int*__restrict__ TS,volatile unsigned*lw,unsigned nxt,cha ...
;     ...
;   if(lw!=nullptr&&tid==0)lw[0]=nxt;
;   {auto rr=__builtin_amdgcn_permlane32_swap(__float_as_uint(l_reg),__float_as_uint(l_reg),false,false);l_reg=__uint_as_float(rr[0])+__uint_as_float(rr[1]);}
;   if(hi==0)wsf[32+r32]=l_reg;asm volatile("s_waitcnt lgkmcnt(0)":::"memory");
.Lfox_drain_join:
	v_mov_b32_e32 v33, v32
	s_nop 1
	v_permlane32_swap_b32_e32 v32, v33
	v_cmp_gt_u32_e32 vcc, 32, v210
	s_and_saveexec_b64 s[8:9], vcc
	s_cbranch_execz .LBB0_1435
	v_add_f32_e32 v32, v32, v33
	ds_write_b32 v215, v32 offset:49280
	s_branch .LBB0_1435
